# qk_post: 8-lane sum-of-squares reduction via 3 DPP adds (quad_perm, quad_perm, row_half_mirror) instead of 3 serialized ds_bpermute round trips
# speedup vs baseline: 1.0090x; 1.0042x over previous
; DI float bflo(unsigned w) { return __uint_as_float(w << 16); }
; DI float bfhi(unsigned w) { return __uint_as_float(w & 0xffff0000u); }
; DI float shx(float v, int o, int lane) { return __int_as_float(__builtin_amdgcn_ds_bpermute((lane ^ o) << 2, __float_as_int(v))); }
; DI void qk_post_token(bf16_t* prow, const float* rope_t, const float* g_qa, const float* g_ka, const float* g_qb, const float* g_kb, int lane) {
;     ...
;         float x[8] = {bflo(w[L].x), bfhi(w[L].x), bflo(w[L].y), bfhi(w[L].y), bflo(w[L].z), bfhi(w[L].z), bflo(w[L].w), bfhi(w[L].w)};
;         float ss = 0.f;
; #pragma unroll
;         for (int e = 0; e < 8; ++e) ss += x[e] * x[e];
;         ss += shx(ss, 1, lane); ss += shx(ss, 2, lane); ss += shx(ss, 4, lane);
;         const float* gp = ty == 0 ? g_qa : ty == 1 ? g_ka : ty == 2 ? g_qb : g_kb;
;         const float rstd = ty < 4 ? 1.0f / sqrtf(ss * (1.f / 64.f) + EPS) : 1.f;
.LBB0_356:
	s_or_b64 exec, exec, s[0:1]
	s_ashr_i32 s0, s24, 31
	s_lshr_b32 s0, s0, 21
	s_add_i32 s0, s24, s0
	s_and_b32 s0, s0, 0xfffff800
	s_sub_i32 s0, s24, s0
	s_ashr_i32 s1, s0, 31
	s_lshl_b64 s[0:1], s[0:1], 8
	v_lshl_add_u64 v[12:13], v[32:33], 0, s[0:1]
	global_load_dwordx4 v[0:3], v[12:13], off offset:48
	global_load_dwordx4 v[4:7], v[12:13], off offset:32
	global_load_dwordx4 v[8:11], v[12:13], off offset:16
	s_nop 0
	global_load_dwordx4 v[12:15], v[12:13], off
	s_waitcnt vmcnt(4)
	v_lshlrev_b32_e32 v58, 16, v28
	v_and_b32_e32 v28, 0xffff0000, v28
	v_mul_f32_e32 v62, v28, v28
	v_lshlrev_b32_e32 v59, 16, v29
	v_fmac_f32_e32 v62, v58, v58
	v_and_b32_e32 v29, 0xffff0000, v29
	v_fmac_f32_e32 v62, v59, v59
	v_lshlrev_b32_e32 v60, 16, v30
	v_fmac_f32_e32 v62, v29, v29
	v_and_b32_e32 v30, 0xffff0000, v30
	v_fmac_f32_e32 v62, v60, v60
	v_lshlrev_b32_e32 v61, 16, v31
	v_fmac_f32_e32 v62, v30, v30
	v_and_b32_e32 v31, 0xffff0000, v31
	v_fmac_f32_e32 v62, v61, v61
	v_fmac_f32_e32 v62, v31, v31
	s_nop 1
	v_add_f32_dpp v63, v62, v62 quad_perm:[1,0,3,2] row_mask:0xf bank_mask:0xf
	s_nop 1
	v_add_f32_dpp v64, v63, v63 quad_perm:[2,3,0,1] row_mask:0xf bank_mask:0xf
	s_nop 1
	v_add_f32_dpp v63, v64, v64 row_half_mirror row_mask:0xf bank_mask:0xf
	v_mov_b32_e32 v62, 1.0
	s_and_saveexec_b64 s[4:5], s[16:17]
	s_cbranch_execz .LBB0_358
	v_mov_b32_e32 v62, v63
	v_fmamk_f32 v62, v62, 0x3c800000, v222
	v_mul_f32_e32 v63, 0x4f800000, v62
	v_cmp_gt_f32_e32 vcc, s25, v62
	s_nop 1
	v_cndmask_b32_e32 v62, v62, v63, vcc
	v_sqrt_f32_e32 v63, v62
	s_nop 0
	v_add_u32_e32 v64, -1, v63
	v_fma_f32 v66, -v64, v63, v62
	v_add_u32_e32 v65, 1, v63
	v_cmp_ge_f32_e64 s[0:1], 0, v66
	s_nop 1
	v_cndmask_b32_e64 v64, v63, v64, s[0:1]
	v_fma_f32 v63, -v65, v63, v62
	v_cmp_lt_f32_e64 s[0:1], 0, v63
	s_nop 1
	v_cndmask_b32_e64 v63, v64, v65, s[0:1]
	v_mul_f32_e32 v64, 0x37800000, v63
	v_cndmask_b32_e32 v63, v63, v64, vcc
	v_cmp_class_f32_e32 vcc, v62, v223
	s_nop 1
	v_cndmask_b32_e32 v62, v63, v62, vcc
	v_div_scale_f32 v63, s[0:1], v62, v62, 1.0
	v_rcp_f32_e32 v64, v63
	s_nop 0
	v_fma_f32 v65, -v63, v64, 1.0
	v_fmac_f32_e32 v64, v65, v64
	v_div_scale_f32 v65, vcc, 1.0, v62, 1.0
	v_mul_f32_e32 v66, v65, v64
	v_fma_f32 v67, -v63, v66, v65
	v_fmac_f32_e32 v66, v67, v64
	v_fma_f32 v63, -v63, v66, v65
	v_div_fmas_f32 v63, v63, v64, v66
	v_div_fixup_f32 v62, v63, v62, 1.0

; DI float bflo(unsigned w) { return __uint_as_float(w << 16); }
; DI float bfhi(unsigned w) { return __uint_as_float(w & 0xffff0000u); }
; DI float shx(float v, int o, int lane) { return __int_as_float(__builtin_amdgcn_ds_bpermute((lane ^ o) << 2, __float_as_int(v))); }
; DI void qk_post_token(bf16_t* prow, const float* rope_t, const float* g_qa, const float* g_ka, const float* g_qb, const float* g_kb, int lane) {
;     ...
;         float x[8] = {bflo(w[L].x), bfhi(w[L].x), bflo(w[L].y), bfhi(w[L].y), bflo(w[L].z), bfhi(w[L].z), bflo(w[L].w), bfhi(w[L].w)};
;         float ss = 0.f;
; #pragma unroll
;         for (int e = 0; e < 8; ++e) ss += x[e] * x[e];
;         ss += shx(ss, 1, lane); ss += shx(ss, 2, lane); ss += shx(ss, 4, lane);
;         const float* gp = ty == 0 ? g_qa : ty == 1 ? g_ka : ty == 2 ? g_qb : g_kb;
;         const float rstd = ty < 4 ? 1.0f / sqrtf(ss * (1.f / 64.f) + EPS) : 1.f;
.LBB0_360:
	s_or_b64 exec, exec, s[0:1]
	s_nop 0
	v_lshlrev_b32_e32 v28, 16, v24
	v_and_b32_e32 v24, 0xffff0000, v24
	v_mul_f32_e32 v56, v24, v24
	s_waitcnt lgkmcnt(0)
	v_lshlrev_b32_e32 v29, 16, v25
	v_fmac_f32_e32 v56, v28, v28
	v_and_b32_e32 v25, 0xffff0000, v25
	v_fmac_f32_e32 v56, v29, v29
	v_lshlrev_b32_e32 v30, 16, v26
	v_fmac_f32_e32 v56, v25, v25
	v_and_b32_e32 v26, 0xffff0000, v26
	v_fmac_f32_e32 v56, v30, v30
	v_lshlrev_b32_e32 v31, 16, v27
	v_fmac_f32_e32 v56, v26, v26
	v_and_b32_e32 v27, 0xffff0000, v27
	v_fmac_f32_e32 v56, v31, v31
	v_fmac_f32_e32 v56, v27, v27
	s_nop 1
	v_add_f32_dpp v57, v56, v56 quad_perm:[1,0,3,2] row_mask:0xf bank_mask:0xf
	s_nop 1
	v_add_f32_dpp v58, v57, v57 quad_perm:[2,3,0,1] row_mask:0xf bank_mask:0xf
	s_nop 1
	v_add_f32_dpp v57, v58, v58 row_half_mirror row_mask:0xf bank_mask:0xf
	v_mov_b32_e32 v56, 1.0
	s_and_saveexec_b64 s[4:5], s[18:19]
	s_cbranch_execz .LBB0_362
	v_mov_b32_e32 v56, v57
	v_fmamk_f32 v56, v56, 0x3c800000, v222
	v_mul_f32_e32 v57, 0x4f800000, v56
	v_cmp_gt_f32_e32 vcc, s25, v56
	s_nop 1
	v_cndmask_b32_e32 v56, v56, v57, vcc
	v_sqrt_f32_e32 v57, v56
	s_nop 0
	v_add_u32_e32 v58, -1, v57
	v_fma_f32 v60, -v58, v57, v56
	v_add_u32_e32 v59, 1, v57
	v_cmp_ge_f32_e64 s[0:1], 0, v60
	s_nop 1
	v_cndmask_b32_e64 v58, v57, v58, s[0:1]
	v_fma_f32 v57, -v59, v57, v56
	v_cmp_lt_f32_e64 s[0:1], 0, v57
	s_nop 1
	v_cndmask_b32_e64 v57, v58, v59, s[0:1]
	v_mul_f32_e32 v58, 0x37800000, v57
	v_cndmask_b32_e32 v57, v57, v58, vcc
	v_cmp_class_f32_e32 vcc, v56, v223
	s_nop 1
	v_cndmask_b32_e32 v56, v57, v56, vcc
	v_div_scale_f32 v57, s[0:1], v56, v56, 1.0
	v_rcp_f32_e32 v58, v57
	s_nop 0
	v_fma_f32 v59, -v57, v58, 1.0
	v_fmac_f32_e32 v58, v59, v58
	v_div_scale_f32 v59, vcc, 1.0, v56, 1.0
	v_mul_f32_e32 v60, v59, v58
	v_fma_f32 v61, -v57, v60, v59
	v_fmac_f32_e32 v60, v61, v58
	v_fma_f32 v57, -v57, v60, v59
	v_div_fmas_f32 v57, v57, v58, v60
	v_div_fixup_f32 v56, v57, v56, 1.0

; DI float bflo(unsigned w) { return __uint_as_float(w << 16); }
; DI float bfhi(unsigned w) { return __uint_as_float(w & 0xffff0000u); }
; DI float shx(float v, int o, int lane) { return __int_as_float(__builtin_amdgcn_ds_bpermute((lane ^ o) << 2, __float_as_int(v))); }
; DI void qk_post_token(bf16_t* prow, const float* rope_t, const float* g_qa, const float* g_ka, const float* g_qb, const float* g_kb, int lane) {
;     ...
;         float x[8] = {bflo(w[L].x), bfhi(w[L].x), bflo(w[L].y), bfhi(w[L].y), bflo(w[L].z), bfhi(w[L].z), bflo(w[L].w), bfhi(w[L].w)};
;         float ss = 0.f;
; #pragma unroll
;         for (int e = 0; e < 8; ++e) ss += x[e] * x[e];
;         ss += shx(ss, 1, lane); ss += shx(ss, 2, lane); ss += shx(ss, 4, lane);
;         const float* gp = ty == 0 ? g_qa : ty == 1 ? g_ka : ty == 2 ? g_qb : g_kb;
;         const float rstd = ty < 4 ? 1.0f / sqrtf(ss * (1.f / 64.f) + EPS) : 1.f;
.LBB0_364:
	s_or_b64 exec, exec, s[0:1]
	s_nop 0
	v_lshlrev_b32_e32 v24, 16, v20
	v_and_b32_e32 v20, 0xffff0000, v20
	s_waitcnt lgkmcnt(0)
	v_lshlrev_b32_e32 v25, 16, v21
	v_and_b32_e32 v26, 0xffff0000, v21
	v_lshlrev_b32_e32 v29, 16, v23
	v_and_b32_e32 v21, 0xffff0000, v23
	v_mul_f32_e32 v23, v20, v20
	v_fmac_f32_e32 v23, v24, v24
	v_fmac_f32_e32 v23, v25, v25
	v_lshlrev_b32_e32 v27, 16, v22
	v_fmac_f32_e32 v23, v26, v26
	v_and_b32_e32 v22, 0xffff0000, v22
	v_fmac_f32_e32 v23, v27, v27
	v_fmac_f32_e32 v23, v22, v22
	v_fmac_f32_e32 v23, v29, v29
	v_fmac_f32_e32 v23, v21, v21
	s_nop 1
	v_add_f32_dpp v28, v23, v23 quad_perm:[1,0,3,2] row_mask:0xf bank_mask:0xf
	s_nop 1
	v_add_f32_dpp v30, v28, v28 quad_perm:[2,3,0,1] row_mask:0xf bank_mask:0xf
	s_nop 1
	v_add_f32_dpp v28, v30, v30 row_half_mirror row_mask:0xf bank_mask:0xf
	v_mov_b32_e32 v23, 1.0
	s_and_saveexec_b64 s[4:5], s[20:21]
	s_cbranch_execz .LBB0_366
	v_mov_b32_e32 v23, v28
	v_fmamk_f32 v23, v23, 0x3c800000, v222
	v_mul_f32_e32 v28, 0x4f800000, v23
	v_cmp_gt_f32_e32 vcc, s25, v23
	s_nop 1
	v_cndmask_b32_e32 v23, v23, v28, vcc
	v_sqrt_f32_e32 v28, v23
	s_nop 0
	v_add_u32_e32 v30, -1, v28
	v_fma_f32 v54, -v30, v28, v23
	v_add_u32_e32 v31, 1, v28
	v_cmp_ge_f32_e64 s[0:1], 0, v54
	s_nop 1
	v_cndmask_b32_e64 v30, v28, v30, s[0:1]
	v_fma_f32 v28, -v31, v28, v23
	v_cmp_lt_f32_e64 s[0:1], 0, v28
	s_nop 1
	v_cndmask_b32_e64 v28, v30, v31, s[0:1]
	v_mul_f32_e32 v30, 0x37800000, v28
	v_cndmask_b32_e32 v28, v28, v30, vcc
	v_cmp_class_f32_e32 vcc, v23, v223
	s_nop 1
	v_cndmask_b32_e32 v23, v28, v23, vcc
	v_div_scale_f32 v28, s[0:1], v23, v23, 1.0
	v_rcp_f32_e32 v30, v28
	s_nop 0
	v_fma_f32 v31, -v28, v30, 1.0
	v_fmac_f32_e32 v30, v31, v30
	v_div_scale_f32 v31, vcc, 1.0, v23, 1.0
	v_mul_f32_e32 v54, v31, v30
	v_fma_f32 v55, -v28, v54, v31
	v_fmac_f32_e32 v54, v55, v30
	v_fma_f32 v28, -v28, v54, v31
	v_div_fmas_f32 v28, v28, v30, v54
	v_div_fixup_f32 v23, v28, v23, 1.0

; DI float bflo(unsigned w) { return __uint_as_float(w << 16); }
; DI float bfhi(unsigned w) { return __uint_as_float(w & 0xffff0000u); }
; DI float shx(float v, int o, int lane) { return __int_as_float(__builtin_amdgcn_ds_bpermute((lane ^ o) << 2, __float_as_int(v))); }
; DI void qk_post_token(bf16_t* prow, const float* rope_t, const float* g_qa, const float* g_ka, const float* g_qb, const float* g_kb, int lane) {
;     ...
;         float x[8] = {bflo(w[L].x), bfhi(w[L].x), bflo(w[L].y), bfhi(w[L].y), bflo(w[L].z), bfhi(w[L].z), bflo(w[L].w), bfhi(w[L].w)};
;         float ss = 0.f;
; #pragma unroll
;         for (int e = 0; e < 8; ++e) ss += x[e] * x[e];
;         ss += shx(ss, 1, lane); ss += shx(ss, 2, lane); ss += shx(ss, 4, lane);
;         const float* gp = ty == 0 ? g_qa : ty == 1 ? g_ka : ty == 2 ? g_qb : g_kb;
;         const float rstd = ty < 4 ? 1.0f / sqrtf(ss * (1.f / 64.f) + EPS) : 1.f;
.LBB0_368:
	s_or_b64 exec, exec, s[0:1]
	s_nop 0
	v_lshlrev_b32_e32 v20, 16, v16
	v_and_b32_e32 v16, 0xffff0000, v16
	v_mul_f32_e32 v24, v16, v16
	s_waitcnt lgkmcnt(1)
	v_lshlrev_b32_e32 v21, 16, v17
	v_fmac_f32_e32 v24, v20, v20
	v_and_b32_e32 v17, 0xffff0000, v17
	v_fmac_f32_e32 v24, v21, v21
	v_lshlrev_b32_e32 v22, 16, v18
	v_fmac_f32_e32 v24, v17, v17
	v_and_b32_e32 v18, 0xffff0000, v18
	v_fmac_f32_e32 v24, v22, v22
	v_lshlrev_b32_e32 v23, 16, v19
	v_fmac_f32_e32 v24, v18, v18
	v_and_b32_e32 v19, 0xffff0000, v19
	v_fmac_f32_e32 v24, v23, v23
	v_fmac_f32_e32 v24, v19, v19
	s_nop 1
	v_add_f32_dpp v25, v24, v24 quad_perm:[1,0,3,2] row_mask:0xf bank_mask:0xf
	s_nop 1
	v_add_f32_dpp v26, v25, v25 quad_perm:[2,3,0,1] row_mask:0xf bank_mask:0xf
	s_nop 1
	v_add_f32_dpp v25, v26, v26 row_half_mirror row_mask:0xf bank_mask:0xf
	v_mov_b32_e32 v24, 1.0
	s_and_saveexec_b64 s[4:5], s[22:23]
	s_cbranch_execz .LBB0_370
	v_mov_b32_e32 v24, v25
	v_fmamk_f32 v24, v24, 0x3c800000, v222
	v_mul_f32_e32 v25, 0x4f800000, v24
	v_cmp_gt_f32_e32 vcc, s25, v24
	s_nop 1
	v_cndmask_b32_e32 v24, v24, v25, vcc
	v_sqrt_f32_e32 v25, v24
	s_nop 0
	v_add_u32_e32 v26, -1, v25
	v_fma_f32 v28, -v26, v25, v24
	v_add_u32_e32 v27, 1, v25
	v_cmp_ge_f32_e64 s[0:1], 0, v28
	s_nop 1
	v_cndmask_b32_e64 v26, v25, v26, s[0:1]
	v_fma_f32 v25, -v27, v25, v24
	v_cmp_lt_f32_e64 s[0:1], 0, v25
	s_nop 1
	v_cndmask_b32_e64 v25, v26, v27, s[0:1]
	v_mul_f32_e32 v26, 0x37800000, v25
	v_cndmask_b32_e32 v25, v25, v26, vcc
	v_cmp_class_f32_e32 vcc, v24, v223
	s_nop 1
	v_cndmask_b32_e32 v24, v25, v24, vcc
	v_div_scale_f32 v25, s[0:1], v24, v24, 1.0
	v_rcp_f32_e32 v26, v25
	s_nop 0
	v_fma_f32 v27, -v25, v26, 1.0
	v_fmac_f32_e32 v26, v27, v26
	v_div_scale_f32 v27, vcc, 1.0, v24, 1.0
	v_mul_f32_e32 v28, v27, v26
	v_fma_f32 v29, -v25, v28, v27
	v_fmac_f32_e32 v28, v29, v26
	v_fma_f32 v25, -v25, v28, v27
	v_div_fmas_f32 v25, v25, v26, v28
	v_div_fixup_f32 v24, v25, v24, 1.0
